# GEMM K-loops P1/P3/P4/P5: static s_setprio 1 for the leading wave half (waves 0-3) instead of the trailing half
# speedup vs baseline: 1.0031x; 1.0018x over previous
.LBB0_175:
	s_mov_b32 s28, s29
	s_ashr_i32 s29, s29, 31
	s_lshl_b64 s[34:35], s[28:29], 20
	s_add_u32 s34, s90, s34
	s_addc_u32 s35, s91, s35
	s_and_b64 s[36:37], s[30:31], exec
	s_mov_b32 s26, s27
	s_cselect_b32 s2, s35, s43
	s_cselect_b32 s29, s34, s42
	s_ashr_i32 s27, s27, 31
	s_lshl_b64 s[36:37], s[26:27], 20
	s_add_u32 s36, s92, s36
	s_addc_u32 s37, s93, s37
	s_and_b64 s[44:45], s[30:31], exec
	s_cselect_b32 s27, s37, s41
	s_cselect_b32 s39, s36, s40
	s_add_u32 s46, s40, 0x100
	s_addc_u32 s47, s41, 0
	s_add_u32 s40, s42, 0x80080
	v_mov_b32_e32 v2, 0
	s_addc_u32 s41, s43, 0
	s_mov_b32 s52, -2
	v_mov_b32_e32 v3, v2
	v_mov_b64_e32 v[4:5], v[2:3]
	v_mov_b64_e32 v[6:7], v[2:3]
	v_mov_b64_e32 v[8:9], v[2:3]
	v_mov_b64_e32 v[18:19], v[2:3]
	v_mov_b64_e32 v[20:21], v[2:3]
	v_mov_b64_e32 v[22:23], v[2:3]
	v_mov_b64_e32 v[24:25], v[2:3]
	v_mov_b64_e32 v[34:35], v[2:3]
	v_mov_b64_e32 v[36:37], v[2:3]
	v_mov_b64_e32 v[38:39], v[2:3]
	v_mov_b64_e32 v[40:41], v[2:3]
	v_mov_b64_e32 v[50:51], v[2:3]
	v_mov_b64_e32 v[52:53], v[2:3]
	v_mov_b64_e32 v[54:55], v[2:3]
	v_mov_b64_e32 v[56:57], v[2:3]
	v_mov_b64_e32 v[10:11], v[2:3]
	v_mov_b64_e32 v[12:13], v[2:3]
	v_mov_b64_e32 v[14:15], v[2:3]
	v_mov_b64_e32 v[16:17], v[2:3]
	v_mov_b64_e32 v[26:27], v[2:3]
	v_mov_b64_e32 v[28:29], v[2:3]
	v_mov_b64_e32 v[30:31], v[2:3]
	v_mov_b64_e32 v[32:33], v[2:3]
	v_mov_b64_e32 v[42:43], v[2:3]
	v_mov_b64_e32 v[44:45], v[2:3]
	v_mov_b64_e32 v[46:47], v[2:3]
	v_mov_b64_e32 v[48:49], v[2:3]
	v_mov_b64_e32 v[66:67], v[2:3]
	v_mov_b64_e32 v[68:69], v[2:3]
	v_mov_b64_e32 v[70:71], v[2:3]
	v_mov_b64_e32 v[72:73], v[2:3]
	v_mov_b64_e32 v[74:75], v[2:3]
	v_mov_b64_e32 v[76:77], v[2:3]
	v_mov_b64_e32 v[86:87], v[2:3]
	v_mov_b64_e32 v[88:89], v[2:3]
	v_mov_b64_e32 v[98:99], v[2:3]
	v_mov_b64_e32 v[100:101], v[2:3]
	v_mov_b64_e32 v[110:111], v[2:3]
	v_mov_b64_e32 v[112:113], v[2:3]
	v_mov_b64_e32 v[130:131], v[2:3]
	v_mov_b64_e32 v[132:133], v[2:3]
	v_mov_b64_e32 v[134:135], v[2:3]
	v_mov_b64_e32 v[136:137], v[2:3]
	v_mov_b64_e32 v[154:155], v[2:3]
	v_mov_b64_e32 v[156:157], v[2:3]
	v_mov_b64_e32 v[158:159], v[2:3]
	v_mov_b64_e32 v[160:161], v[2:3]
	v_mov_b64_e32 v[90:91], v[2:3]
	v_mov_b64_e32 v[92:93], v[2:3]
	v_mov_b64_e32 v[94:95], v[2:3]
	v_mov_b64_e32 v[96:97], v[2:3]
	v_mov_b64_e32 v[114:115], v[2:3]
	v_mov_b64_e32 v[116:117], v[2:3]
	v_mov_b64_e32 v[118:119], v[2:3]
	v_mov_b64_e32 v[120:121], v[2:3]
	v_mov_b64_e32 v[138:139], v[2:3]
	v_mov_b64_e32 v[140:141], v[2:3]
	v_mov_b64_e32 v[142:143], v[2:3]
	v_mov_b64_e32 v[144:145], v[2:3]
	v_mov_b64_e32 v[162:163], v[2:3]
	v_mov_b64_e32 v[164:165], v[2:3]
	v_mov_b64_e32 v[166:167], v[2:3]
	v_mov_b64_e32 v[168:169], v[2:3]
	v_add_u32_e32 v212, 0x18000, v218
	v_add_u32_e32 v213, 0x1c000, v218
	s_cmp_eq_u64 s[24:25], 0
	s_cbranch_scc1 .Lhp_skip_1
	s_setprio 1

.LBB0_650:
	s_ashr_i32 s15, s14, 31
	s_lshl_b64 s[18:19], s[14:15], 20
	s_add_u32 s18, s92, s18
	s_addc_u32 s19, s93, s19
	s_and_b64 s[20:21], s[16:17], exec
	s_cselect_b32 s15, s19, s29
	s_cselect_b32 s23, s18, s28
	s_ashr_i32 s13, s12, 31
	s_lshl_b64 s[20:21], s[12:13], 20
	s_add_u32 s20, s94, s20
	s_addc_u32 s21, s95, s21
	s_and_b64 s[30:31], s[16:17], exec
	s_cselect_b32 s13, s21, s27
	s_cselect_b32 s43, s20, s26
	s_add_u32 s44, s26, 0x100
	s_addc_u32 s45, s27, 0
	s_add_u32 s26, s28, 0x80080
	v_mov_b32_e32 v2, 0
	s_addc_u32 s27, s29, 0
	s_mov_b32 s46, -2
	s_waitcnt lgkmcnt(0)
	v_mov_b32_e32 v3, v2
	v_mov_b64_e32 v[4:5], v[2:3]
	v_mov_b64_e32 v[6:7], v[2:3]
	v_mov_b64_e32 v[8:9], v[2:3]
	v_mov_b64_e32 v[18:19], v[2:3]
	v_mov_b64_e32 v[20:21], v[2:3]
	v_mov_b64_e32 v[22:23], v[2:3]
	v_mov_b64_e32 v[24:25], v[2:3]
	v_mov_b64_e32 v[34:35], v[2:3]
	v_mov_b64_e32 v[36:37], v[2:3]
	v_mov_b64_e32 v[38:39], v[2:3]
	v_mov_b64_e32 v[40:41], v[2:3]
	v_mov_b64_e32 v[50:51], v[2:3]
	v_mov_b64_e32 v[52:53], v[2:3]
	v_mov_b64_e32 v[54:55], v[2:3]
	v_mov_b64_e32 v[56:57], v[2:3]
	v_mov_b64_e32 v[10:11], v[2:3]
	v_mov_b64_e32 v[12:13], v[2:3]
	v_mov_b64_e32 v[14:15], v[2:3]
	v_mov_b64_e32 v[16:17], v[2:3]
	v_mov_b64_e32 v[26:27], v[2:3]
	v_mov_b64_e32 v[28:29], v[2:3]
	v_mov_b64_e32 v[30:31], v[2:3]
	v_mov_b64_e32 v[32:33], v[2:3]
	v_mov_b64_e32 v[42:43], v[2:3]
	v_mov_b64_e32 v[44:45], v[2:3]
	v_mov_b64_e32 v[46:47], v[2:3]
	v_mov_b64_e32 v[48:49], v[2:3]
	v_mov_b64_e32 v[58:59], v[2:3]
	v_mov_b64_e32 v[60:61], v[2:3]
	v_mov_b64_e32 v[62:63], v[2:3]
	v_mov_b64_e32 v[64:65], v[2:3]
	v_mov_b64_e32 v[66:67], v[2:3]
	v_mov_b64_e32 v[68:69], v[2:3]
	v_mov_b64_e32 v[70:71], v[2:3]
	v_mov_b64_e32 v[72:73], v[2:3]
	v_mov_b64_e32 v[82:83], v[2:3]
	v_mov_b64_e32 v[84:85], v[2:3]
	v_mov_b64_e32 v[86:87], v[2:3]
	v_mov_b64_e32 v[88:89], v[2:3]
	v_mov_b64_e32 v[98:99], v[2:3]
	v_mov_b64_e32 v[100:101], v[2:3]
	v_mov_b64_e32 v[102:103], v[2:3]
	v_mov_b64_e32 v[104:105], v[2:3]
	v_mov_b64_e32 v[114:115], v[2:3]
	v_mov_b64_e32 v[116:117], v[2:3]
	v_mov_b64_e32 v[118:119], v[2:3]
	v_mov_b64_e32 v[120:121], v[2:3]
	v_mov_b64_e32 v[74:75], v[2:3]
	v_mov_b64_e32 v[76:77], v[2:3]
	v_mov_b64_e32 v[78:79], v[2:3]
	v_mov_b64_e32 v[80:81], v[2:3]
	v_mov_b64_e32 v[90:91], v[2:3]
	v_mov_b64_e32 v[92:93], v[2:3]
	v_mov_b64_e32 v[94:95], v[2:3]
	v_mov_b64_e32 v[96:97], v[2:3]
	v_mov_b64_e32 v[106:107], v[2:3]
	v_mov_b64_e32 v[108:109], v[2:3]
	v_mov_b64_e32 v[110:111], v[2:3]
	v_mov_b64_e32 v[112:113], v[2:3]
	v_mov_b64_e32 v[122:123], v[2:3]
	v_mov_b64_e32 v[124:125], v[2:3]
	v_mov_b64_e32 v[126:127], v[2:3]
	v_mov_b64_e32 v[128:129], v[2:3]
	v_add_u32_e32 v192, 0x18000, v195
	v_add_u32_e32 v193, 0x1c000, v195
	s_cmp_eq_u64 s[10:11], 0
	s_cbranch_scc1 .Lhp_skip_3
	s_setprio 1

.LBB0_807:
	s_mov_b32 s18, s19
	s_ashr_i32 s19, s19, 31
	s_lshl_b64 s[22:23], s[18:19], 20
	s_add_u32 s22, s70, s22
	s_addc_u32 s23, s71, s23
	s_and_b64 s[24:25], s[20:21], exec
	s_mov_b32 s16, s17
	s_cselect_b32 s19, s23, s35
	s_cselect_b32 s51, s22, s34
	s_ashr_i32 s17, s17, 31
	s_lshl_b64 s[24:25], s[16:17], 20
	s_add_u32 s24, s84, s24
	s_addc_u32 s25, s85, s25
	s_and_b64 s[36:37], s[20:21], exec
	s_cselect_b32 s17, s25, s31
	s_cselect_b32 s52, s24, s30
	s_add_u32 s53, s30, 0x100
	s_addc_u32 s54, s31, 0
	s_add_u32 s30, s34, 0x80080
	v_mov_b32_e32 v2, 0
	s_addc_u32 s31, s35, 0
	s_mov_b32 s55, -2
	v_mov_b32_e32 v3, v2
	v_mov_b64_e32 v[4:5], v[2:3]
	v_mov_b64_e32 v[6:7], v[2:3]
	v_mov_b64_e32 v[8:9], v[2:3]
	v_mov_b64_e32 v[18:19], v[2:3]
	v_mov_b64_e32 v[20:21], v[2:3]
	v_mov_b64_e32 v[22:23], v[2:3]
	v_mov_b64_e32 v[24:25], v[2:3]
	v_mov_b64_e32 v[34:35], v[2:3]
	v_mov_b64_e32 v[36:37], v[2:3]
	v_mov_b64_e32 v[38:39], v[2:3]
	v_mov_b64_e32 v[40:41], v[2:3]
	v_mov_b64_e32 v[50:51], v[2:3]
	v_mov_b64_e32 v[52:53], v[2:3]
	v_mov_b64_e32 v[54:55], v[2:3]
	v_mov_b64_e32 v[56:57], v[2:3]
	v_mov_b64_e32 v[10:11], v[2:3]
	v_mov_b64_e32 v[12:13], v[2:3]
	v_mov_b64_e32 v[14:15], v[2:3]
	v_mov_b64_e32 v[16:17], v[2:3]
	v_mov_b64_e32 v[26:27], v[2:3]
	v_mov_b64_e32 v[28:29], v[2:3]
	v_mov_b64_e32 v[30:31], v[2:3]
	v_mov_b64_e32 v[32:33], v[2:3]
	v_mov_b64_e32 v[42:43], v[2:3]
	v_mov_b64_e32 v[44:45], v[2:3]
	v_mov_b64_e32 v[46:47], v[2:3]
	v_mov_b64_e32 v[48:49], v[2:3]
	v_mov_b64_e32 v[58:59], v[2:3]
	v_mov_b64_e32 v[60:61], v[2:3]
	v_mov_b64_e32 v[62:63], v[2:3]
	v_mov_b64_e32 v[64:65], v[2:3]
	v_mov_b64_e32 v[66:67], v[2:3]
	v_mov_b64_e32 v[68:69], v[2:3]
	v_mov_b64_e32 v[70:71], v[2:3]
	v_mov_b64_e32 v[72:73], v[2:3]
	v_mov_b64_e32 v[82:83], v[2:3]
	v_mov_b64_e32 v[84:85], v[2:3]
	v_mov_b64_e32 v[86:87], v[2:3]
	v_mov_b64_e32 v[88:89], v[2:3]
	v_mov_b64_e32 v[98:99], v[2:3]
	v_mov_b64_e32 v[100:101], v[2:3]
	v_mov_b64_e32 v[102:103], v[2:3]
	v_mov_b64_e32 v[104:105], v[2:3]
	v_mov_b64_e32 v[114:115], v[2:3]
	v_mov_b64_e32 v[116:117], v[2:3]
	v_mov_b64_e32 v[118:119], v[2:3]
	v_mov_b64_e32 v[120:121], v[2:3]
	v_mov_b64_e32 v[74:75], v[2:3]
	v_mov_b64_e32 v[76:77], v[2:3]
	v_mov_b64_e32 v[78:79], v[2:3]
	v_mov_b64_e32 v[80:81], v[2:3]
	v_mov_b64_e32 v[90:91], v[2:3]
	v_mov_b64_e32 v[92:93], v[2:3]
	v_mov_b64_e32 v[94:95], v[2:3]
	v_mov_b64_e32 v[96:97], v[2:3]
	v_mov_b64_e32 v[106:107], v[2:3]
	v_mov_b64_e32 v[108:109], v[2:3]
	v_mov_b64_e32 v[110:111], v[2:3]
	v_mov_b64_e32 v[112:113], v[2:3]
	v_mov_b64_e32 v[122:123], v[2:3]
	v_mov_b64_e32 v[124:125], v[2:3]
	v_mov_b64_e32 v[126:127], v[2:3]
	v_mov_b64_e32 v[128:129], v[2:3]
	v_add_u32_e32 v148, 0x18000, v150
	v_add_u32_e32 v149, 0x1c000, v150
	s_cmp_eq_u64 s[12:13], 0
	s_cbranch_scc1 .Lhp_skip_4
	s_setprio 1

.LBB0_1030:
	v_and_b32_e32 v1, 15, v0
	v_and_b32_e32 v14, 48, v0
	v_lshlrev_b32_e32 v16, 2, v0
	s_lshl_b32 s24, s4, 6
	v_lshl_or_b32 v15, v1, 6, v14
	s_lshl_b32 s4, s4, 13
	v_and_b32_e32 v16, 32, v16
	s_and_b32 s18, s17, 3
	v_bitop3_b32 v15, v15, s4, v16 bitop3:0xde
	v_lshlrev_b32_e32 v17, 6, v0
	s_movk_i32 s4, 0x3c0
	v_and_or_b32 v14, v17, s4, v14
	s_lshl_b32 s4, s18, 12
	v_bitop3_b32 v14, s4, v14, v16 bitop3:0xf6
	s_mov_b64 s[4:5], 0x80
	s_add_i32 m0, s20, 0x18000
	v_lshl_add_u64 v[8:9], v[8:9], 0, s[4:5]
	s_waitcnt vmcnt(2)
	s_barrier
	global_load_lds_dwordx4 v[8:9], off
	v_lshl_add_u64 v[6:7], v[6:7], 0, s[4:5]
	s_add_i32 m0, s20, 0x1a000
	s_add_i32 s25, s20, 0x8000
	s_add_i32 s26, s20, 0xa000
	global_load_lds_dwordx4 v[6:7], off
	v_lshl_add_u64 v[4:5], v[4:5], 0, s[4:5]
	s_mov_b32 m0, s25
	s_add_u32 s8, s0, 0x200080
	global_load_lds_dwordx4 v[4:5], off
	v_lshl_add_u64 v[2:3], v[2:3], 0, s[4:5]
	s_mov_b32 m0, s26
	s_addc_u32 s9, s1, 0
	global_load_lds_dwordx4 v[2:3], off
	s_add_i32 m0, s20, 0x1c000
	v_lshl_add_u64 v[2:3], s[8:9], 0, v[130:131]
	global_load_lds_dwordx4 v[2:3], off
	v_lshl_add_u64 v[2:3], s[8:9], 0, v[132:133]
	s_add_i32 m0, s20, 0x1e000
	s_add_u32 s8, s70, s13
	global_load_lds_dwordx4 v[2:3], off
	s_addc_u32 s9, s71, 0
	s_add_u32 s27, s8, 0xc000100
	v_lshlrev_b32_e32 v2, 11, v0
	s_addc_u32 s28, s9, 0
	v_and_b32_e32 v2, 0xc0000, v2
	v_lshlrev_b32_e32 v4, 14, v13
	s_add_u32 s8, s70, s10
	v_or3_b32 v2, v10, v2, v4
	s_addc_u32 s9, s71, s11
	v_add_u32_e32 v2, v2, v11
	v_mov_b32_e32 v3, v131
	v_lshl_add_u64 v[2:3], s[8:9], 0, v[2:3]
	s_mov_b64 s[10:11], 0x2200080
	v_lshl_add_u64 v[134:135], v[2:3], 0, s[10:11]
	v_lshlrev_b32_e32 v2, 7, v12
	v_and_b32_e32 v2, 0x1c0000, v2
	v_or3_b32 v2, v10, v2, v4
	s_waitcnt vmcnt(6)
	v_add_u32_e32 v2, v2, v11
	v_mov_b32_e32 v3, v131
	s_add_i32 s34, 0, 0x10000
	s_add_i32 s36, 0, 0x14000
	s_add_i32 s38, 0, 0x18000
	s_add_i32 s40, 0, 0x1c000
	v_lshl_add_u64 v[2:3], s[8:9], 0, v[2:3]
	v_add_u32_e32 v139, s34, v14
	v_add_u32_e32 v140, s36, v14
	s_add_i32 s34, s34, s12
	s_add_i32 s36, s36, s12
	v_add_u32_e32 v142, s38, v14
	v_add_u32_e32 v143, s40, v14
	s_add_i32 s38, s38, s12
	s_add_i32 s40, s40, s12
	v_readlane_b32 s44, v242, 16
	v_lshrrev_b32_e32 v138, 2, v0
	v_or_b32_e32 v162, s24, v1
	v_lshl_add_u64 v[136:137], v[2:3], 0, s[10:11]
	s_mov_b32 s29, -2
	s_mov_b64 s[10:11], 0
	v_add_u32_e32 v141, 0, v15
	s_add_i32 s30, s20, 0xc000
	s_add_i32 s31, s20, 0xe000
	s_add_i32 s35, s34, 0x2000
	s_add_i32 s37, s36, 0x2000
	s_add_i32 s39, s38, 0x2000
	s_add_i32 s41, s40, 0x2000
	v_mov_b32_e32 v2, v131
	v_mov_b32_e32 v3, v131
	v_mov_b32_e32 v4, v131
	v_mov_b32_e32 v5, v131
	v_mov_b32_e32 v6, v131
	v_mov_b32_e32 v7, v131
	v_mov_b32_e32 v8, v131
	v_mov_b32_e32 v9, v131
	v_mov_b32_e32 v18, v131
	v_mov_b32_e32 v19, v131
	v_mov_b32_e32 v20, v131
	v_mov_b32_e32 v21, v131
	v_mov_b32_e32 v22, v131
	v_mov_b32_e32 v23, v131
	v_mov_b32_e32 v24, v131
	v_mov_b32_e32 v25, v131
	v_mov_b32_e32 v34, v131
	v_mov_b32_e32 v35, v131
	v_mov_b32_e32 v36, v131
	v_mov_b32_e32 v37, v131
	v_mov_b32_e32 v38, v131
	v_mov_b32_e32 v39, v131
	v_mov_b32_e32 v40, v131
	v_mov_b32_e32 v41, v131
	v_mov_b32_e32 v50, v131
	v_mov_b32_e32 v51, v131
	v_mov_b32_e32 v52, v131
	v_mov_b32_e32 v53, v131
	v_mov_b32_e32 v54, v131
	v_mov_b32_e32 v55, v131
	v_mov_b32_e32 v56, v131
	v_mov_b32_e32 v57, v131
	v_mov_b32_e32 v10, v131
	v_mov_b32_e32 v11, v131
	v_mov_b32_e32 v12, v131
	v_mov_b32_e32 v13, v131
	v_mov_b32_e32 v14, v131
	v_mov_b32_e32 v15, v131
	v_mov_b32_e32 v16, v131
	v_mov_b32_e32 v17, v131
	v_mov_b32_e32 v26, v131
	v_mov_b32_e32 v27, v131
	v_mov_b32_e32 v28, v131
	v_mov_b32_e32 v29, v131
	v_mov_b32_e32 v30, v131
	v_mov_b32_e32 v31, v131
	v_mov_b32_e32 v32, v131
	v_mov_b32_e32 v33, v131
	v_mov_b32_e32 v42, v131
	v_mov_b32_e32 v43, v131
	v_mov_b32_e32 v44, v131
	v_mov_b32_e32 v45, v131
	v_mov_b32_e32 v46, v131
	v_mov_b32_e32 v47, v131
	v_mov_b32_e32 v48, v131
	v_mov_b32_e32 v49, v131
	v_mov_b32_e32 v58, v131
	v_mov_b32_e32 v59, v131
	v_mov_b32_e32 v60, v131
	v_mov_b32_e32 v61, v131
	v_mov_b32_e32 v62, v131
	v_mov_b32_e32 v63, v131
	v_mov_b32_e32 v64, v131
	v_mov_b32_e32 v65, v131
	v_mov_b32_e32 v66, v131
	v_mov_b32_e32 v67, v131
	v_mov_b32_e32 v68, v131
	v_mov_b32_e32 v69, v131
	v_mov_b32_e32 v70, v131
	v_mov_b32_e32 v71, v131
	v_mov_b32_e32 v72, v131
	v_mov_b32_e32 v73, v131
	v_mov_b32_e32 v82, v131
	v_mov_b32_e32 v83, v131
	v_mov_b32_e32 v84, v131
	v_mov_b32_e32 v85, v131
	v_mov_b32_e32 v86, v131
	v_mov_b32_e32 v87, v131
	v_mov_b32_e32 v88, v131
	v_mov_b32_e32 v89, v131
	v_mov_b32_e32 v98, v131
	v_mov_b32_e32 v99, v131
	v_mov_b32_e32 v100, v131
	v_mov_b32_e32 v101, v131
	v_mov_b32_e32 v102, v131
	v_mov_b32_e32 v103, v131
	v_mov_b32_e32 v104, v131
	v_mov_b32_e32 v105, v131
	v_mov_b32_e32 v114, v131
	v_mov_b32_e32 v115, v131
	v_mov_b32_e32 v116, v131
	v_mov_b32_e32 v117, v131
	v_mov_b32_e32 v118, v131
	v_mov_b32_e32 v119, v131
	v_mov_b32_e32 v120, v131
	v_mov_b32_e32 v121, v131
	v_mov_b32_e32 v74, v131
	v_mov_b32_e32 v75, v131
	v_mov_b32_e32 v76, v131
	v_mov_b32_e32 v77, v131
	v_mov_b32_e32 v78, v131
	v_mov_b32_e32 v79, v131
	v_mov_b32_e32 v80, v131
	v_mov_b32_e32 v81, v131
	v_mov_b32_e32 v90, v131
	v_mov_b32_e32 v91, v131
	v_mov_b32_e32 v92, v131
	v_mov_b32_e32 v93, v131
	v_mov_b32_e32 v94, v131
	v_mov_b32_e32 v95, v131
	v_mov_b32_e32 v96, v131
	v_mov_b32_e32 v97, v131
	v_mov_b32_e32 v106, v131
	v_mov_b32_e32 v107, v131
	v_mov_b32_e32 v108, v131
	v_mov_b32_e32 v109, v131
	v_mov_b32_e32 v110, v131
	v_mov_b32_e32 v111, v131
	v_mov_b32_e32 v112, v131
	v_mov_b32_e32 v113, v131
	v_mov_b32_e32 v122, v131
	v_mov_b32_e32 v123, v131
	v_mov_b32_e32 v124, v131
	v_mov_b32_e32 v125, v131
	v_mov_b32_e32 v126, v131
	v_mov_b32_e32 v127, v131
	v_mov_b32_e32 v128, v131
	v_mov_b32_e32 v129, v131
	v_readlane_b32 s45, v242, 17
	s_barrier
	s_cmpk_gt_u32 s19, 0xff
	s_cbranch_scc1 .Lhp_skip_5
	s_setprio 1
